# out-proj sample tile: all 32 fragment loads issued up front with counted vmcnt waits; gate/residual loads hoisted before the LDS reduction; slab reads batched (sum order unchanged)
# baseline (speedup 1.0000x reference)
; #define LAS __attribute__((address_space(3)))
; __device__ __forceinline__ int crow(int r, int hi) { return (r & 3) + 8 * (r >> 2) + 4 * hi; }
; __device__ __forceinline__ void g2_sample_tile(const bf16_t* __restrict__ Y, const bf16_t* __restrict__ Wt, const float* xs  , const bf16_t* xbs  , float* outs  , bf16_t* outbs  , const float* __restrict__ gate, ...
;     const int row0 = (tile >> 4) * 64, col0 = (tile & 15) * 64, m = lane & 31, kq = lane >> 5;
;     f32x16 acc[2][2];
; #pragma unroll
;     for (int i2 = 0; i2 < 2; ++i2)
; #pragma unroll
;         for (int j2 = 0; j2 < 2; ++j2)
; #pragma unroll
;             for (int i = 0; i < 16; ++i) acc[i2][j2][i] = 0.f;
;     const bf16_t* ap = Y + (size_t)(MP + row0 + m) * D + wave * 128 + kq * 8;
;     const bf16_t* bp = Wt + (size_t)(col0 + m) * D + wave * 128 + kq * 8;
; #pragma unroll
;     for (int ks = 0; ks < 8; ++ks) {
;         const bf16x8 a0 = *(const bf16x8*)(ap + ks * 16), a1 = *(const bf16x8*)(ap + 32 * D + ks * 16), b0 = *(const bf16x8*)(bp + ks * 16), b1 = *(const bf16x8*)(bp + 32 * D + ks * 16);
;         acc[0][0] = __builtin_amdgcn_mfma_f32_32x32x16_bf16(a0, b0, acc[0][0], 0, 0, 0); acc[0][1] = __builtin_amdgcn_mfma_f32_32x32x16_bf16(a0, b1, acc[0][1], 0, 0, 0);
;         acc[1][0] = __builtin_amdgcn_mfma_f32_32x32x16_bf16(a1, b0, acc[1][0], 0, 0, 0); acc[1][1] = __builtin_amdgcn_mfma_f32_32x32x16_bf16(a1, b1, acc[1][1], 0, 0, 0);
;     }
;     LAS float* slab = (LAS float*)lds + wave * 4096;
; #pragma unroll
;     for (int i2 = 0; i2 < 2; ++i2)
; #pragma unroll
;         for (int j2 = 0; j2 < 2; ++j2)
; #pragma unroll
;             for (int i = 0; i < 16; ++i) slab[(32 * i2 + crow(i, kq)) * 64 + 32 * j2 + m] = acc[i2][j2][i];
;     __syncthreads();
.LBB0_594:
	s_and_b32 s21, s23, 0xffffffc0
	v_add_u32_e32 v0, s21, v78
	v_ashrrev_i32_e32 v1, 31, v0
	s_and_b32 s20, s22, 0x3c0
	v_lshlrev_b64 v[0:1], 11, v[0:1]
	v_lshl_add_u64 v[72:73], v[64:65], 0, v[0:1]
	v_or_b32_e32 v0, s20, v69
	v_lshlrev_b32_e32 v172, 11, v0
	global_load_dwordx4 v[0:3], v[72:73], off
	v_add_co_u32_e32 v74, vcc, 0x10000, v72
	v_lshl_add_u64 v[70:71], v[66:67], 0, v[172:173]
	s_nop 0
	v_addc_co_u32_e32 v75, vcc, 0, v73, vcc
	v_add_co_u32_e32 v76, vcc, 0x10000, v70
	global_load_dwordx4 v[16:19], v[74:75], off
	global_load_dwordx4 v[4:7], v[70:71], off
	v_addc_co_u32_e32 v77, vcc, 0, v71, vcc
	global_load_dwordx4 v[20:23], v[76:77], off
	global_load_dwordx4 v[90:93], v[72:73], off offset:32
	global_load_dwordx4 v[94:97], v[74:75], off offset:32
	global_load_dwordx4 v[98:101], v[70:71], off offset:32
	global_load_dwordx4 v[102:105], v[76:77], off offset:32
	global_load_dwordx4 v[106:109], v[72:73], off offset:64
	global_load_dwordx4 v[110:113], v[74:75], off offset:64
	global_load_dwordx4 v[114:117], v[70:71], off offset:64
	global_load_dwordx4 v[118:121], v[76:77], off offset:64
	global_load_dwordx4 v[122:125], v[72:73], off offset:96
	global_load_dwordx4 v[126:129], v[74:75], off offset:96
	global_load_dwordx4 v[132:135], v[70:71], off offset:96
	global_load_dwordx4 v[136:139], v[76:77], off offset:96
	global_load_dwordx4 v[140:143], v[72:73], off offset:128
	global_load_dwordx4 v[144:147], v[74:75], off offset:128
	global_load_dwordx4 v[148:151], v[70:71], off offset:128
	global_load_dwordx4 v[152:155], v[76:77], off offset:128
	global_load_dwordx4 v[156:159], v[72:73], off offset:160
	global_load_dwordx4 v[160:163], v[74:75], off offset:160
	global_load_dwordx4 v[164:167], v[70:71], off offset:160
	global_load_dwordx4 v[168:171], v[76:77], off offset:160
	global_load_dwordx4 v[182:185], v[72:73], off offset:192
	global_load_dwordx4 v[186:189], v[74:75], off offset:192
	global_load_dwordx4 v[190:193], v[70:71], off offset:192
	global_load_dwordx4 v[194:197], v[76:77], off offset:192
	global_load_dwordx4 v[198:201], v[72:73], off offset:224
	global_load_dwordx4 v[202:205], v[74:75], off offset:224
	global_load_dwordx4 v[236:239], v[70:71], off offset:224
	global_load_dwordx4 v[240:243], v[76:77], off offset:224
	s_lshl_b32 s86, s20, 2
	v_lshlrev_b32_e32 v172, 2, v68
	s_waitcnt vmcnt(29)
	v_mfma_f32_32x32x16_bf16 v[32:47], v[0:3], v[4:7], 0
	s_waitcnt vmcnt(28)
	v_mfma_f32_32x32x16_bf16 v[48:63], v[0:3], v[20:23], 0
	v_mfma_f32_32x32x16_bf16 v[0:15], v[16:19], v[4:7], 0
	v_mfma_f32_32x32x16_bf16 v[16:31], v[16:19], v[20:23], 0
	s_waitcnt vmcnt(24)
	v_mfma_f32_32x32x16_bf16 v[32:47], v[90:93], v[98:101], v[32:47]
	v_mfma_f32_32x32x16_bf16 v[48:63], v[90:93], v[102:105], v[48:63]
	v_mfma_f32_32x32x16_bf16 v[0:15], v[94:97], v[98:101], v[0:15]
	v_mfma_f32_32x32x16_bf16 v[16:31], v[94:97], v[102:105], v[16:31]
	s_waitcnt vmcnt(20)
	v_mfma_f32_32x32x16_bf16 v[32:47], v[106:109], v[114:117], v[32:47]
	v_mfma_f32_32x32x16_bf16 v[48:63], v[106:109], v[118:121], v[48:63]
	v_mfma_f32_32x32x16_bf16 v[0:15], v[110:113], v[114:117], v[0:15]
	v_mfma_f32_32x32x16_bf16 v[16:31], v[110:113], v[118:121], v[16:31]
	s_waitcnt vmcnt(16)
	v_mfma_f32_32x32x16_bf16 v[32:47], v[122:125], v[132:135], v[32:47]
	v_mfma_f32_32x32x16_bf16 v[48:63], v[122:125], v[136:139], v[48:63]
	v_mfma_f32_32x32x16_bf16 v[0:15], v[126:129], v[132:135], v[0:15]
	v_mfma_f32_32x32x16_bf16 v[16:31], v[126:129], v[136:139], v[16:31]
	s_waitcnt vmcnt(12)
	v_mfma_f32_32x32x16_bf16 v[32:47], v[140:143], v[148:151], v[32:47]
	v_mfma_f32_32x32x16_bf16 v[48:63], v[140:143], v[152:155], v[48:63]
	v_mfma_f32_32x32x16_bf16 v[0:15], v[144:147], v[148:151], v[0:15]
	v_mfma_f32_32x32x16_bf16 v[16:31], v[144:147], v[152:155], v[16:31]
	s_waitcnt vmcnt(8)
	v_mfma_f32_32x32x16_bf16 v[32:47], v[156:159], v[164:167], v[32:47]
	v_mfma_f32_32x32x16_bf16 v[48:63], v[156:159], v[168:171], v[48:63]
	v_mfma_f32_32x32x16_bf16 v[0:15], v[160:163], v[164:167], v[0:15]
	v_mfma_f32_32x32x16_bf16 v[16:31], v[160:163], v[168:171], v[16:31]
	s_waitcnt vmcnt(4)
	v_mfma_f32_32x32x16_bf16 v[32:47], v[182:185], v[190:193], v[32:47]
	v_mfma_f32_32x32x16_bf16 v[48:63], v[182:185], v[194:197], v[48:63]
	v_mfma_f32_32x32x16_bf16 v[0:15], v[186:189], v[190:193], v[0:15]
	v_mfma_f32_32x32x16_bf16 v[16:31], v[186:189], v[194:197], v[16:31]
	s_waitcnt vmcnt(0)
	v_mfma_f32_32x32x16_bf16 v[32:47], v[198:201], v[236:239], v[32:47]
	v_mfma_f32_32x32x16_bf16 v[48:63], v[198:201], v[240:243], v[48:63]
	s_nop 11
	ds_write2_b32 v79, v32, v48 offset1:32
	ds_write2_b32 v79, v33, v49 offset0:64 offset1:96
	ds_write2_b32 v79, v34, v50 offset0:128 offset1:160
	ds_write2_b32 v79, v35, v51 offset0:192 offset1:224
	v_mfma_f32_32x32x16_bf16 v[0:15], v[202:205], v[236:239], v[0:15]
	v_add_u32_e32 v32, 0x800, v79
	ds_write2_b32 v32, v36, v52 offset1:32
	ds_write2_b32 v32, v37, v53 offset0:64 offset1:96
	ds_write2_b32 v32, v38, v54 offset0:128 offset1:160
	ds_write2_b32 v32, v39, v55 offset0:192 offset1:224
	v_add_u32_e32 v32, 0x1000, v79
	ds_write2_b32 v32, v40, v56 offset1:32
	ds_write2_b32 v32, v41, v57 offset0:64 offset1:96
	ds_write2_b32 v32, v42, v58 offset0:128 offset1:160
	ds_write2_b32 v32, v43, v59 offset0:192 offset1:224
	v_add_u32_e32 v32, 0x1800, v79
	ds_write2_b32 v32, v44, v60 offset1:32
	ds_write2_b32 v32, v45, v61 offset0:64 offset1:96
	ds_write2_b32 v32, v46, v62 offset0:128 offset1:160
	ds_write2_b32 v32, v47, v63 offset0:192 offset1:224
	v_add_u32_e32 v32, 0x2000, v79
	v_mfma_f32_32x32x16_bf16 v[16:31], v[202:205], v[240:243], v[16:31]
	s_nop 11
	ds_write2_b32 v32, v0, v16 offset1:32
	ds_write2_b32 v32, v1, v17 offset0:64 offset1:96
	ds_write2_b32 v32, v2, v18 offset0:128 offset1:160
	ds_write2_b32 v32, v3, v19 offset0:192 offset1:224
	v_add_u32_e32 v0, 0x2800, v79
	ds_write2_b32 v0, v4, v20 offset1:32
	ds_write2_b32 v0, v5, v21 offset0:64 offset1:96
	ds_write2_b32 v0, v6, v22 offset0:128 offset1:160
	ds_write2_b32 v0, v7, v23 offset0:192 offset1:224
	v_add_u32_e32 v0, 0x3000, v79
	ds_write2_b32 v0, v8, v24 offset1:32
	ds_write2_b32 v0, v9, v25 offset0:64 offset1:96
	ds_write2_b32 v0, v10, v26 offset0:128 offset1:160
	ds_write2_b32 v0, v11, v27 offset0:192 offset1:224
	v_add_u32_e32 v0, 0x3800, v79
	ds_write2_b32 v0, v12, v28 offset1:32
	ds_write2_b32 v0, v13, v29 offset0:64 offset1:96
	ds_write2_b32 v0, v14, v30 offset0:128 offset1:160
	ds_write2_b32 v0, v15, v31 offset0:192 offset1:224
	s_waitcnt lgkmcnt(0)
	s_barrier
; #define LAS __attribute__((address_space(3)))
; __device__ __forceinline__ void g2_sample_tile(const bf16_t* __restrict__ Y, const bf16_t* __restrict__ Wt, const float* xs  , const bf16_t* xbs  , float* outs  , bf16_t* outbs  , const float* __restrict__ gate, ...
;     ...
;     const int r = tid >> 3, c8 = (tid & 7) * 8;
;     f32x4 s0 = {0.f, 0.f, 0.f, 0.f}, s1 = {0.f, 0.f, 0.f, 0.f};
; #pragma unroll
;     for (int w = 0; w < 8; ++w) { const LAS float* sp = (const LAS float*)lds + w * 4096 + r * 64 + c8; s0 += *(const LAS f32x4*)sp; s1 += *(const LAS f32x4*)(sp + 4); }
;     const int srow = row0 + r, nidx = NPB + (srow >> 3);
;     const size_t ro = (size_t)srow * D + col0 + c8; const float* gp = gate + (size_t)nidx * 3072 + col0 + c8;
;     const f32x4 g0 = *(const f32x4*)gp, g1 = *(const f32x4*)(gp + 4);
;     f32x4 x0, x1;
;     if (xs) { x0 = *(const f32x4*)(xs + ro); x1 = *(const f32x4*)(xs + ro + 4); }
;     else { const u32x4 w = __builtin_nontemporal_load((const u32x4*)(xbs + ro));
;         x0 = (f32x4){__uint_as_float(w.x << 16), __uint_as_float(w.x & 0xffff0000u), __uint_as_float(w.y << 16), __uint_as_float(w.y & 0xffff0000u)};
;         x1 = (f32x4){__uint_as_float(w.z << 16), __uint_as_float(w.z & 0xffff0000u), __uint_as_float(w.w << 16), __uint_as_float(w.w & 0xffff0000u)}; }
;     const f32x4 v0 = x0 + g0 * s0, v1 = x1 + g1 * s1;
;     if (outbs) { u32x4 w; w.x = pk_bf16(v0[0], v0[1]); w.y = pk_bf16(v0[2], v0[3]); w.z = pk_bf16(v1[0], v1[1]); w.w = pk_bf16(v1[2], v1[3]); *(u32x4*)(outbs + ro) = w; }
;     else { *(f32x4*)(outs + ro) = v0; *(f32x4*)(outs + ro + 4) = v1; }
	v_add_u32_e32 v0, s21, v80
	v_ashrrev_i32_e32 v1, 3, v0
	v_add_u32_e32 v2, 4, v1
	v_ashrrev_i32_e32 v1, 31, v0
	v_lshlrev_b64 v[16:17], 10, v[0:1]
	v_or_b32_e32 v0, s20, v16
	v_or_b32_e32 v16, v0, v68
	v_mov_b64_e32 v[0:1], s[4:5]
	s_movk_i32 s21, 0x3000
	v_mad_i64_i32 v[0:1], s[26:27], v2, s21, v[0:1]
	v_lshl_add_u64 v[0:1], v[0:1], 0, s[86:87]
	v_lshl_add_u64 v[4:5], v[0:1], 0, v[172:173]
	v_lshl_add_u64 v[18:19], v[16:17], 1, s[10:11]
	global_load_dwordx4 v[106:109], v[4:5], off offset:16
	global_load_dwordx4 v[110:113], v[4:5], off
	global_load_dwordx4 v[114:117], v[18:19], off nt
	ds_read_b128 v[20:23], v81
	ds_read_b128 v[24:27], v81 offset:16
	ds_read_b128 v[28:31], v81 offset:16384
	ds_read_b128 v[32:35], v81 offset:16400
	ds_read_b128 v[36:39], v81 offset:32768
	ds_read_b128 v[40:43], v81 offset:32784
	ds_read_b128 v[44:47], v81 offset:49152
	ds_read_b128 v[48:51], v81 offset:49168
	ds_read_b128 v[52:55], v82
	ds_read_b128 v[56:59], v83
	ds_read_b128 v[60:63], v84
	ds_read_b128 v[90:93], v85
	ds_read_b128 v[94:97], v86
	ds_read_b128 v[98:101], v87
	ds_read_b128 v[102:105], v88
	ds_read_b128 v[118:121], v89
	v_readlane_b32 s26, v255, 8
	v_readlane_b32 s27, v255, 9
	s_mov_b64 s[20:21], -1
	s_waitcnt lgkmcnt(14)
	v_pk_add_f32 v[8:9], v[22:23], 0 op_sel_hi:[1,0]
	v_pk_add_f32 v[10:11], v[20:21], 0 op_sel_hi:[1,0]
	v_pk_add_f32 v[6:7], v[26:27], 0 op_sel_hi:[1,0]
	v_pk_add_f32 v[4:5], v[24:25], 0 op_sel_hi:[1,0]
	s_waitcnt lgkmcnt(12)
	v_pk_add_f32 v[8:9], v[8:9], v[30:31]
	v_pk_add_f32 v[10:11], v[10:11], v[28:29]
	v_pk_add_f32 v[6:7], v[6:7], v[34:35]
	v_pk_add_f32 v[4:5], v[4:5], v[32:33]
	s_waitcnt lgkmcnt(10)
	v_pk_add_f32 v[8:9], v[8:9], v[38:39]
	v_pk_add_f32 v[10:11], v[10:11], v[36:37]
	v_pk_add_f32 v[6:7], v[6:7], v[42:43]
	v_pk_add_f32 v[4:5], v[4:5], v[40:41]
	s_waitcnt lgkmcnt(8)
	v_pk_add_f32 v[8:9], v[8:9], v[46:47]
	v_pk_add_f32 v[10:11], v[10:11], v[44:45]
	v_pk_add_f32 v[6:7], v[6:7], v[50:51]
	v_pk_add_f32 v[4:5], v[4:5], v[48:49]
	s_waitcnt lgkmcnt(6)
	v_pk_add_f32 v[8:9], v[8:9], v[54:55]
	v_pk_add_f32 v[10:11], v[10:11], v[52:53]
	v_pk_add_f32 v[6:7], v[6:7], v[58:59]
	v_pk_add_f32 v[4:5], v[4:5], v[56:57]
	s_waitcnt lgkmcnt(4)
	v_pk_add_f32 v[8:9], v[8:9], v[62:63]
	v_pk_add_f32 v[10:11], v[10:11], v[60:61]
	v_pk_add_f32 v[6:7], v[6:7], v[92:93]
	v_pk_add_f32 v[4:5], v[4:5], v[90:91]
	s_waitcnt lgkmcnt(2)
	v_pk_add_f32 v[8:9], v[8:9], v[96:97]
	v_pk_add_f32 v[10:11], v[10:11], v[94:95]
	v_pk_add_f32 v[6:7], v[6:7], v[100:101]
	v_pk_add_f32 v[4:5], v[4:5], v[98:99]
	s_waitcnt lgkmcnt(0)
	v_pk_add_f32 v[12:13], v[8:9], v[104:105]
	v_pk_add_f32 v[14:15], v[10:11], v[102:103]
	v_pk_add_f32 v[10:11], v[4:5], v[118:119]
	v_pk_add_f32 v[8:9], v[6:7], v[120:121]
	s_and_b64 vcc, exec, s[26:27]
	s_waitcnt vmcnt(0)
	v_lshlrev_b32_e32 v22, 16, v114
	v_and_b32_e32 v23, 0xffff0000, v114
	v_lshlrev_b32_e32 v18, 16, v115
	v_and_b32_e32 v19, 0xffff0000, v115
	v_lshlrev_b32_e32 v24, 16, v116
	v_and_b32_e32 v25, 0xffff0000, v116
	v_lshlrev_b32_e32 v20, 16, v117
	v_and_b32_e32 v21, 0xffff0000, v117
	v_pk_fma_f32 v[4:5], v[14:15], v[110:111], v[22:23]
	v_pk_fma_f32 v[6:7], v[12:13], v[112:113], v[18:19]
	v_pk_fma_f32 v[0:1], v[10:11], v[106:107], v[24:25]
	v_pk_fma_f32 v[2:3], v[8:9], v[108:109], v[20:21]
	s_cbranch_vccz .LBB0_596
	v_readlane_b32 s20, v254, 24
	v_readlane_b32 s21, v254, 25
	s_nop 1
	v_lshl_add_u64 v[8:9], v[16:17], 2, s[20:21]
	global_store_dwordx4 v[8:9], v[4:7], off
	global_store_dwordx4 v[8:9], v[0:3], off offset:16
	s_mov_b64 s[20:21], 0
